# attention: stick-breaking items claimed two per dequeue atomic (half the B-queue atomics)
# baseline (speedup 1.0000x reference)
; __device__ __forceinline__ void phase_attn(const Ctx& C, const float* relb  , int layer) {
;     ...
;       for (int k = 0; k < 8; ++k) { const int x = (((int)blockIdx.x & 7) + k * (1 + 2 * (((int)blockIdx.x >> 3) & 3))) & 7;
;           unsigned* qb_ = (unsigned*)(ws_ + WS_BAR) + WQ_WORD + 64 * (8 * layer + x);
;           unsigned* qa_ = (unsigned*)(ws_ + WS_BAR) + WQ_WORD + 64 * (16 + 8 * layer + x);
;           for (;;) {
;               unsigned idx = 0;
;               if (lane == 0) idx = __hip_atomic_fetch_add(qb_, 1u, __ATOMIC_RELAXED, __HIP_MEMORY_SCOPE_AGENT);
;               idx = (unsigned)__builtin_amdgcn_readfirstlane((int)idx);
;               if (idx >= (unsigned)per_q) break;
.Lq_k0:
	v_readlane_b32 s2, v255, 7
	s_mul_i32 s2, s100, s2
	v_readlane_b32 s3, v254, 0
	s_add_i32 s2, s2, s3
	s_mov_b32 s1, s78
	s_and_b32 s78, s2, 7
	s_lshl_b32 s2, s78, 6
	v_readlane_b32 s3, v255, 47
	s_or_b32 s10, s2, s3
	s_lshl_b64 s[2:3], s[10:11], 2
	v_readlane_b32 s10, v255, 43
	s_add_u32 s20, s10, s2
	v_readlane_b32 s2, v255, 44
	s_addc_u32 s21, s2, s3
	s_lshl_b32 s2, s78, 12
	s_mul_i32 s3, s78, 0x1800000
	s_add_u32 s12, s14, s3
	s_addc_u32 s13, s15, 0
	v_lshl_add_u64 v[134:135], v[116:117], 1, s[12:13]
	s_mov_b64 s[12:13], 0x1400
	s_lshl_b32 s10, s78, 14
	v_lshl_add_u64 v[98:99], v[134:135], 0, s[12:13]
	v_or_b32_e32 v136, s2, v114
	v_lshl_add_u64 v[100:101], v[130:131], 0, s[10:11]
	s_mov_b32 s99, -1
	v_mov_b32_e32 v229, 2
	s_lshl_b32 s101, s78, 2
	s_add_i32 s101, s101, 0x23800
	v_mov_b32_e32 v226, s101
	ds_read_b32 v227, v226
	s_waitcnt lgkmcnt(0)
	v_readfirstlane_b32 s98, v227
	s_nop 0
	s_cmp_lg_u32 s98, 0
	s_cbranch_scc1 .LBB0_299
	s_branch .LBB0_265

; #define LAS __attribute__((address_space(3)))
; __device__ __forceinline__ void attnB_wave(LAS unsigned char* st, const bf16* QKV, bf16* O, float* sso, int b, int h, int qi, int lane) {
;     const int ql = lane & 31, hi = lane >> 5, q0 = 32 * qi;
;     const size_t tb = (size_t)b * SEQ;
;     const AtdAddr A = atd_addr(QKV + tb * 3072 + 1536 + h * 64, QKV + tb * 3072 + 2048 + 512 + h * 64, lane);
;     const bf16* Qp = QKV + (tb + q0 + ql) * 3072 + 1024 + h * 64 + hi * 8;
;     bf16x8 qf[4];
; #pragma unroll
;     for (int d0 = 0; d0 < 4; ++d0) qf[d0] = *(const bf16x8*)(Qp + d0 * 16);
;     const int n = qi + 1;
;     ATD_DMA(A, st, qi, 0);
;     if (n > 1) ATD_DMA(A, st, qi - 1, 1);
; __device__ __forceinline__ void phase_attn(const Ctx& C, const float* relb  , int layer) {
;     ...
;           for (;;) {
;               unsigned idx = 0;
;               if (lane == 0) idx = __hip_atomic_fetch_add(qb_, 1u, __ATOMIC_RELAXED, __HIP_MEMORY_SCOPE_AGENT);
;               idx = (unsigned)__builtin_amdgcn_readfirstlane((int)idx);
;               if (idx >= (unsigned)per_q) break;
;               const int bh = x * 8 + (int)(idx >> 7), qi = 127 - (int)(idx & 127);
;               attnB_wave(st, QKV, O, sso, bh >> 3, bh & 7, qi, lane);
.LBB0_265:
	s_cmp_eq_u32 s99, -1
	s_cbranch_scc1 .Lb_fetch
	s_mov_b32 s10, s99
	s_mov_b32 s99, -1
	s_branch .Lb_proc
.Lb_fetch:
	v_mov_b32_e32 v226, s101
	ds_read_b32 v227, v226
	s_waitcnt lgkmcnt(0)
	v_readfirstlane_b32 s98, v227
	s_nop 0
	s_cmp_lg_u32 s98, 0
	s_cbranch_scc1 .LBB0_299
	v_mov_b32_e32 v0, 0
	s_and_saveexec_b64 s[12:13], s[36:37]
	s_cbranch_execz .LBB0_267
	s_waitcnt lgkmcnt(0)
	v_mov_b64_e32 v[0:1], s[20:21]
	flat_atomic_add v0, v[0:1], v229 sc0
.LBB0_267:
	s_or_b64 exec, exec, s[12:13]
	s_waitcnt vmcnt(0) lgkmcnt(0)
	v_readfirstlane_b32 s10, v0
	s_nop 0
	s_add_i32 s99, s10, 1
	s_cmpk_gt_u32 s10, 0x3ff
	s_mov_b64 s[12:13], -1
	s_cbranch_scc1 .LBB0_264
.Lb_proc:
	s_and_b32 s3, s10, 0x7f
	s_lshr_b32 s10, s10, 1
	s_and_b32 s10, s10, 0x1c0
	s_lshl_b32 s12, s10, 1
	s_mov_b32 s13, s11
	s_xor_b32 s81, s3, 0x7f
	v_lshl_add_u64 v[0:1], v[134:135], 0, s[12:13]
	s_lshl_b32 s80, s81, 5
	v_lshl_add_u64 v[102:103], v[118:119], 1, v[0:1]
	v_lshl_add_u64 v[104:105], v[120:121], 1, v[0:1]
	v_lshl_add_u64 v[0:1], v[98:99], 0, s[12:13]
	v_lshl_add_u64 v[106:107], v[122:123], 1, v[0:1]
	v_lshl_add_u64 v[108:109], v[124:125], 1, v[0:1]
	v_or_b32_e32 v80, s80, v136
	v_mov_b64_e32 v[0:1], s[14:15]
	v_mad_u64_u32 v[0:1], s[78:79], v80, s0, v[0:1]
	v_lshl_add_u64 v[0:1], v[0:1], 0, s[12:13]
	v_lshl_add_u64 v[0:1], v[128:129], 1, v[0:1]
	s_mul_i32 s10, s81, 0x30000
	flat_load_dwordx4 v[64:67], v[0:1] offset:2048
	flat_load_dwordx4 v[68:71], v[0:1] offset:2080
	flat_load_dwordx4 v[72:75], v[0:1] offset:2112
	flat_load_dwordx4 v[76:79], v[0:1] offset:2144
	v_lshl_add_u64 v[0:1], v[102:103], 0, s[10:11]
	s_mov_b32 m0, s33
	v_lshl_add_u64 v[2:3], v[0:1], 0, s[22:23]
	global_load_lds_dwordx4 v[2:3], off
	v_lshl_add_u64 v[2:3], v[104:105], 0, s[10:11]
	s_add_i32 s13, s33, 0x400
	v_lshl_add_u64 v[4:5], v[2:3], 0, s[74:75]
	s_mov_b32 m0, s13
	s_add_i32 s82, s33, 0x800
	global_load_lds_dwordx4 v[4:5], off
	v_lshl_add_u64 v[0:1], v[0:1], 0, s[76:77]
	s_mov_b32 m0, s82
	s_add_i32 s83, s33, 0xc00
	global_load_lds_dwordx4 v[0:1], off
	v_lshl_add_u64 v[0:1], v[2:3], 0, s[24:25]
	s_mov_b32 m0, s83
	s_add_i32 s86, s33, 0x1000
	global_load_lds_dwordx4 v[0:1], off
	v_lshl_add_u64 v[0:1], v[106:107], 0, s[10:11]
	s_mov_b32 m0, s86
	v_lshl_add_u64 v[2:3], v[108:109], 0, s[10:11]
	s_add_i32 s87, s33, 0x1400
	global_load_lds_dwordx4 v[0:1], off
	v_lshl_add_u64 v[4:5], v[2:3], 0, s[26:27]
	s_mov_b32 m0, s87
	s_add_i32 s88, s33, 0x1800
	global_load_lds_dwordx4 v[4:5], off
	v_lshl_add_u64 v[0:1], v[0:1], 0, s[28:29]
	s_mov_b32 m0, s88
	s_add_i32 s89, s33, 0x1c00
	global_load_lds_dwordx4 v[0:1], off
	v_lshl_add_u64 v[0:1], v[2:3], 0, s[30:31]
	s_mov_b32 m0, s89
	s_cmpk_eq_i32 s3, 0x7f
	global_load_lds_dwordx4 v[0:1], off
	s_cselect_b64 s[78:79], -1, 0
	s_cmpk_lg_i32 s3, 0x7f
	s_cselect_b64 s[84:85], -1, 0
	s_and_b64 vcc, exec, s[78:79]
	s_cbranch_vccnz .LBB0_270
	s_mul_i32 s10, s81, 0x18000
	s_add_i32 s10, s10, 0xfffe8000
	s_lshl_b64 s[90:91], s[10:11], 1
	v_lshl_add_u64 v[0:1], v[102:103], 0, s[90:91]
	v_lshl_add_u64 v[2:3], v[0:1], 0, s[22:23]
	s_add_i32 m0, s33, 0x2000
	v_readlane_b32 s10, v255, 32
	global_load_lds_dwordx4 v[2:3], off
	v_lshl_add_u64 v[2:3], v[104:105], 0, s[90:91]
	v_lshl_add_u64 v[4:5], v[2:3], 0, s[74:75]
	s_mov_b32 m0, s10
	v_readlane_b32 s10, v255, 33
	global_load_lds_dwordx4 v[4:5], off
	v_lshl_add_u64 v[0:1], v[0:1], 0, s[76:77]
	s_mov_b32 m0, s10
	v_readlane_b32 s10, v255, 34
	global_load_lds_dwordx4 v[0:1], off
	v_lshl_add_u64 v[0:1], v[2:3], 0, s[24:25]
	s_mov_b32 m0, s10
	v_readlane_b32 s10, v255, 35
	global_load_lds_dwordx4 v[0:1], off
	v_lshl_add_u64 v[0:1], v[106:107], 0, s[90:91]
	s_mov_b32 m0, s10
	v_lshl_add_u64 v[2:3], v[108:109], 0, s[90:91]
	v_readlane_b32 s10, v255, 36
	global_load_lds_dwordx4 v[0:1], off
	v_lshl_add_u64 v[4:5], v[2:3], 0, s[26:27]
	s_mov_b32 m0, s10
	v_readlane_b32 s10, v255, 37
	global_load_lds_dwordx4 v[4:5], off
	v_lshl_add_u64 v[0:1], v[0:1], 0, s[28:29]
	s_mov_b32 m0, s10
	s_mov_b64 s[90:91], 0x1000
	global_load_lds_dwordx4 v[0:1], off
	v_lshl_add_u64 v[0:1], v[2:3], 0, s[30:31]
	s_mov_b32 m0, s8
	s_nop 0
	global_load_lds_dwordx4 v[0:1], off
